# phase 3 spatial gating: the four b_spatial loads hoisted to the item's load batch (was a serialized load+wait per 16-row group behind the previous store)
# speedup vs baseline: 1.0045x; 1.0045x over previous
.LBB0_11:
	s_mul_i32 s6, s34, 24
	s_ashr_i32 s7, s6, 31
	v_lshl_add_u64 v[8:9], s[6:7], 2, v[4:5]
	v_mov_b32_e32 v47, v41
	s_mov_b32 s14, 0
	v_mov_b32_e32 v10, 0
	v_mov_b32_e32 v11, v3
	v_mov_b32_e32 v12, 0
	v_mov_b32_e32 v13, v3
	v_min_u32_e32 v80, 23, v67
	v_lshlrev_b32_e32 v80, 2, v80
	v_mov_b32_e32 v81, 0
	v_lshl_add_u64 v[254:255], s[6:7], 2, v[80:81]
	v_lshl_add_u64 v[254:255], s[54:55], 0, v[254:255]
	global_load_dword v252, v[254:255], off
	v_lshl_add_u64 v[82:83], s[6:7], 2, v[80:81]
	v_lshl_add_u64 v[82:83], s[52:53], 0, v[82:83]
	v_add_u32_e32 v84, -14, v41
	v_mul_u32_u24_e64 v84, v84, s33
	v_mov_b32_e32 v85, 0
	v_lshl_add_u64 v[82:83], v[84:85], 0, v[82:83]
	s_mov_b64 s[14:15], 0xc000
	v_add_u32_e32 v84, 0x12000, v35
	global_load_dword v86, v[82:83], off nt
	v_lshl_add_u64 v[82:83], v[82:83], 0, s[14:15]
	global_load_dword v87, v[82:83], off nt
	v_lshl_add_u64 v[82:83], v[82:83], 0, s[14:15]
	global_load_dword v88, v[82:83], off nt
	v_lshl_add_u64 v[82:83], v[82:83], 0, s[14:15]
	global_load_dword v89, v[82:83], off nt
	v_lshl_add_u64 v[82:83], v[82:83], 0, s[14:15]
	global_load_dword v90, v[82:83], off nt
	v_lshl_add_u64 v[82:83], v[82:83], 0, s[14:15]
	global_load_dword v91, v[82:83], off nt
	v_lshl_add_u64 v[82:83], v[82:83], 0, s[14:15]
	global_load_dword v92, v[82:83], off nt
	v_lshl_add_u64 v[82:83], v[82:83], 0, s[14:15]
	global_load_dword v93, v[82:83], off nt
	v_lshl_add_u64 v[82:83], v[82:83], 0, s[14:15]
	global_load_dword v94, v[82:83], off nt
	v_lshl_add_u64 v[82:83], v[82:83], 0, s[14:15]
	global_load_dword v95, v[82:83], off nt
	v_lshl_add_u64 v[82:83], v[82:83], 0, s[14:15]
	global_load_dword v96, v[82:83], off nt
	v_lshl_add_u64 v[82:83], v[82:83], 0, s[14:15]
	global_load_dword v97, v[82:83], off nt
	v_lshl_add_u64 v[82:83], v[82:83], 0, s[14:15]
	global_load_dword v98, v[82:83], off nt
	v_lshl_add_u64 v[82:83], v[82:83], 0, s[14:15]
	global_load_dword v99, v[82:83], off nt
	v_lshl_add_u64 v[82:83], v[82:83], 0, s[14:15]
	global_load_dword v100, v[82:83], off nt
	v_lshl_add_u64 v[82:83], v[82:83], 0, s[14:15]
	global_load_dword v101, v[82:83], off nt
	v_lshl_add_u64 v[82:83], v[82:83], 0, s[14:15]
	global_load_dword v102, v[82:83], off nt
	v_lshl_add_u64 v[82:83], v[82:83], 0, s[14:15]
	global_load_dword v103, v[82:83], off nt
	v_lshl_add_u64 v[82:83], v[82:83], 0, s[14:15]
	global_load_dword v104, v[82:83], off nt
	v_lshl_add_u64 v[82:83], v[82:83], 0, s[14:15]
	global_load_dword v105, v[82:83], off nt
	v_lshl_add_u64 v[82:83], v[82:83], 0, s[14:15]
	global_load_dword v106, v[82:83], off nt
	v_lshl_add_u64 v[82:83], v[82:83], 0, s[14:15]
	global_load_dword v107, v[82:83], off nt
	v_lshl_add_u64 v[82:83], v[82:83], 0, s[14:15]
	global_load_dword v108, v[82:83], off nt
	v_lshl_add_u64 v[82:83], v[82:83], 0, s[14:15]
	global_load_dword v109, v[82:83], off nt
	v_lshl_add_u64 v[82:83], v[82:83], 0, s[14:15]
	global_load_dword v110, v[82:83], off nt
	v_lshl_add_u64 v[82:83], v[82:83], 0, s[14:15]
	global_load_dword v111, v[82:83], off nt
	v_lshl_add_u64 v[82:83], v[82:83], 0, s[14:15]
	global_load_dword v112, v[82:83], off nt
	v_lshl_add_u64 v[82:83], v[82:83], 0, s[14:15]
	global_load_dword v113, v[82:83], off nt
	v_lshl_add_u64 v[82:83], v[82:83], 0, s[14:15]
	global_load_dword v114, v[82:83], off nt
	v_lshl_add_u64 v[82:83], v[82:83], 0, s[14:15]
	global_load_dword v115, v[82:83], off nt
	v_lshl_add_u64 v[82:83], v[82:83], 0, s[14:15]
	global_load_dword v116, v[82:83], off nt
	v_lshl_add_u64 v[82:83], v[82:83], 0, s[14:15]
	global_load_dword v117, v[82:83], off nt
	v_lshl_add_u64 v[82:83], v[82:83], 0, s[14:15]
	global_load_dword v118, v[82:83], off nt
	v_lshl_add_u64 v[82:83], v[82:83], 0, s[14:15]
	global_load_dword v119, v[82:83], off nt
	v_lshl_add_u64 v[82:83], v[82:83], 0, s[14:15]
	global_load_dword v120, v[82:83], off nt
	v_lshl_add_u64 v[82:83], v[82:83], 0, s[14:15]
	global_load_dword v121, v[82:83], off nt
	v_lshl_add_u64 v[82:83], v[82:83], 0, s[14:15]
	global_load_dword v122, v[82:83], off nt
	v_lshl_add_u64 v[82:83], v[82:83], 0, s[14:15]
	global_load_dword v123, v[82:83], off nt
	v_lshl_add_u64 v[82:83], v[82:83], 0, s[14:15]
	global_load_dword v124, v[82:83], off nt
	v_lshl_add_u64 v[82:83], v[82:83], 0, s[14:15]
	global_load_dword v125, v[82:83], off nt
	v_lshl_add_u64 v[82:83], v[82:83], 0, s[14:15]
	global_load_dword v126, v[82:83], off nt
	v_lshl_add_u64 v[82:83], v[82:83], 0, s[14:15]
	global_load_dword v127, v[82:83], off nt
	v_lshl_add_u64 v[82:83], v[82:83], 0, s[14:15]
	global_load_dword v128, v[82:83], off nt
	v_lshl_add_u64 v[82:83], v[82:83], 0, s[14:15]
	global_load_dword v129, v[82:83], off nt
	v_lshl_add_u64 v[82:83], v[82:83], 0, s[14:15]
	global_load_dword v130, v[82:83], off nt
	v_lshl_add_u64 v[82:83], v[82:83], 0, s[14:15]
	global_load_dword v131, v[82:83], off nt
	v_lshl_add_u64 v[82:83], v[82:83], 0, s[14:15]
	global_load_dword v132, v[82:83], off nt
	v_lshl_add_u64 v[82:83], v[82:83], 0, s[14:15]
	global_load_dword v133, v[82:83], off nt
	v_lshl_add_u64 v[82:83], v[82:83], 0, s[14:15]
	global_load_dword v134, v[82:83], off nt
	v_lshl_add_u64 v[82:83], v[82:83], 0, s[14:15]
	global_load_dword v135, v[82:83], off nt
	v_lshl_add_u64 v[82:83], v[82:83], 0, s[14:15]
	global_load_dword v136, v[82:83], off nt
	v_lshl_add_u64 v[82:83], v[82:83], 0, s[14:15]
	global_load_dword v137, v[82:83], off nt
	v_lshl_add_u64 v[82:83], v[82:83], 0, s[14:15]
	global_load_dword v138, v[82:83], off nt
	v_lshl_add_u64 v[82:83], v[82:83], 0, s[14:15]
	global_load_dword v139, v[82:83], off nt
	v_lshl_add_u64 v[82:83], v[82:83], 0, s[14:15]
	global_load_dword v140, v[82:83], off nt
	v_lshl_add_u64 v[82:83], v[82:83], 0, s[14:15]
	global_load_dword v141, v[82:83], off nt
	v_lshl_add_u64 v[82:83], v[82:83], 0, s[14:15]
	v_add_u32_e32 v85, 0, v84
	ds_read2st64_b32 v[150:151], v85 offset1:16
	ds_read2st64_b32 v[152:153], v85 offset0:32 offset1:48
	v_add_u32_e32 v85, 8, v84
	ds_read2st64_b32 v[154:155], v85 offset1:16
	ds_read2st64_b32 v[156:157], v85 offset0:32 offset1:48
	v_add_u32_e32 v85, 16, v84
	ds_read2st64_b32 v[158:159], v85 offset1:16
	ds_read2st64_b32 v[160:161], v85 offset0:32 offset1:48
	v_add_u32_e32 v85, 24, v84
	ds_read2st64_b32 v[162:163], v85 offset1:16
	ds_read2st64_b32 v[164:165], v85 offset0:32 offset1:48
	v_add_u32_e32 v85, 32, v84
	ds_read2st64_b32 v[166:167], v85 offset1:16
	ds_read2st64_b32 v[168:169], v85 offset0:32 offset1:48
	v_add_u32_e32 v85, 40, v84
	ds_read2st64_b32 v[170:171], v85 offset1:16
	ds_read2st64_b32 v[172:173], v85 offset0:32 offset1:48
	v_add_u32_e32 v85, 48, v84
	ds_read2st64_b32 v[174:175], v85 offset1:16
	ds_read2st64_b32 v[176:177], v85 offset0:32 offset1:48
	v_add_u32_e32 v85, 56, v84
	ds_read2st64_b32 v[178:179], v85 offset1:16
	ds_read2st64_b32 v[180:181], v85 offset0:32 offset1:48
	s_waitcnt lgkmcnt(0)
	v_add_u32_e32 v85, 64, v84
	ds_read2st64_b32 v[182:183], v85 offset1:16
	ds_read2st64_b32 v[184:185], v85 offset0:32 offset1:48
	v_add_u32_e32 v85, 72, v84
	ds_read2st64_b32 v[186:187], v85 offset1:16
	ds_read2st64_b32 v[188:189], v85 offset0:32 offset1:48
	v_add_u32_e32 v85, 80, v84
	ds_read2st64_b32 v[190:191], v85 offset1:16
	ds_read2st64_b32 v[192:193], v85 offset0:32 offset1:48
	v_add_u32_e32 v85, 88, v84
	ds_read2st64_b32 v[194:195], v85 offset1:16
	ds_read2st64_b32 v[196:197], v85 offset0:32 offset1:48
	v_add_u32_e32 v85, 96, v84
	ds_read2st64_b32 v[198:199], v85 offset1:16
	ds_read2st64_b32 v[200:201], v85 offset0:32 offset1:48
	v_add_u32_e32 v85, 104, v84
	ds_read2st64_b32 v[202:203], v85 offset1:16
	ds_read2st64_b32 v[204:205], v85 offset0:32 offset1:48
	v_add_u32_e32 v85, 112, v84
	ds_read2st64_b32 v[206:207], v85 offset1:16
	ds_read2st64_b32 v[208:209], v85 offset0:32 offset1:48
	v_add_u32_e32 v85, 120, v84
	ds_read2st64_b32 v[210:211], v85 offset1:16
	ds_read2st64_b32 v[212:213], v85 offset0:32 offset1:48
	s_waitcnt vmcnt(55)
	v_pk_fma_f32 v[10:11], v[86:87], v[150:151], v[10:11] op_sel_hi:[0,1,1]
	v_pk_fma_f32 v[12:13], v[86:87], v[152:153], v[12:13] op_sel_hi:[0,1,1]
	global_load_dword v142, v[82:83], off nt
	v_lshl_add_u64 v[82:83], v[82:83], 0, s[14:15]
	s_waitcnt vmcnt(55)
	v_pk_fma_f32 v[10:11], v[86:87], v[154:155], v[10:11] op_sel:[1,0,0] op_sel_hi:[1,1,1]
	v_pk_fma_f32 v[12:13], v[86:87], v[156:157], v[12:13] op_sel:[1,0,0] op_sel_hi:[1,1,1]
	global_load_dword v143, v[82:83], off nt
	v_lshl_add_u64 v[82:83], v[82:83], 0, s[14:15]
	s_waitcnt vmcnt(55)
	v_pk_fma_f32 v[10:11], v[88:89], v[158:159], v[10:11] op_sel_hi:[0,1,1]
	v_pk_fma_f32 v[12:13], v[88:89], v[160:161], v[12:13] op_sel_hi:[0,1,1]
	global_load_dword v144, v[82:83], off nt
	v_lshl_add_u64 v[82:83], v[82:83], 0, s[14:15]
	s_waitcnt vmcnt(55)
	v_pk_fma_f32 v[10:11], v[88:89], v[162:163], v[10:11] op_sel:[1,0,0] op_sel_hi:[1,1,1]
	v_pk_fma_f32 v[12:13], v[88:89], v[164:165], v[12:13] op_sel:[1,0,0] op_sel_hi:[1,1,1]
	global_load_dword v145, v[82:83], off nt
	v_lshl_add_u64 v[82:83], v[82:83], 0, s[14:15]
	s_waitcnt vmcnt(55)
	v_pk_fma_f32 v[10:11], v[90:91], v[166:167], v[10:11] op_sel_hi:[0,1,1]
	v_pk_fma_f32 v[12:13], v[90:91], v[168:169], v[12:13] op_sel_hi:[0,1,1]
	global_load_dword v146, v[82:83], off nt
	v_lshl_add_u64 v[82:83], v[82:83], 0, s[14:15]
	s_waitcnt vmcnt(55)
	v_pk_fma_f32 v[10:11], v[90:91], v[170:171], v[10:11] op_sel:[1,0,0] op_sel_hi:[1,1,1]
	v_pk_fma_f32 v[12:13], v[90:91], v[172:173], v[12:13] op_sel:[1,0,0] op_sel_hi:[1,1,1]
	global_load_dword v147, v[82:83], off nt
	v_lshl_add_u64 v[82:83], v[82:83], 0, s[14:15]
	s_waitcnt vmcnt(55)
	v_pk_fma_f32 v[10:11], v[92:93], v[174:175], v[10:11] op_sel_hi:[0,1,1]
	v_pk_fma_f32 v[12:13], v[92:93], v[176:177], v[12:13] op_sel_hi:[0,1,1]
	global_load_dword v148, v[82:83], off nt
	v_lshl_add_u64 v[82:83], v[82:83], 0, s[14:15]
	s_waitcnt vmcnt(55)
	v_pk_fma_f32 v[10:11], v[92:93], v[178:179], v[10:11] op_sel:[1,0,0] op_sel_hi:[1,1,1]
	v_pk_fma_f32 v[12:13], v[92:93], v[180:181], v[12:13] op_sel:[1,0,0] op_sel_hi:[1,1,1]
	global_load_dword v149, v[82:83], off nt
	v_lshl_add_u64 v[82:83], v[82:83], 0, s[14:15]
	s_waitcnt lgkmcnt(0)
	v_add_u32_e32 v85, 128, v84
	ds_read2st64_b32 v[150:151], v85 offset1:16
	ds_read2st64_b32 v[152:153], v85 offset0:32 offset1:48
	v_add_u32_e32 v85, 136, v84
	ds_read2st64_b32 v[154:155], v85 offset1:16
	ds_read2st64_b32 v[156:157], v85 offset0:32 offset1:48
	v_add_u32_e32 v85, 144, v84
	ds_read2st64_b32 v[158:159], v85 offset1:16
	ds_read2st64_b32 v[160:161], v85 offset0:32 offset1:48
	v_add_u32_e32 v85, 152, v84
	ds_read2st64_b32 v[162:163], v85 offset1:16
	ds_read2st64_b32 v[164:165], v85 offset0:32 offset1:48
	v_add_u32_e32 v85, 160, v84
	ds_read2st64_b32 v[166:167], v85 offset1:16
	ds_read2st64_b32 v[168:169], v85 offset0:32 offset1:48
	v_add_u32_e32 v85, 168, v84
	ds_read2st64_b32 v[170:171], v85 offset1:16
	ds_read2st64_b32 v[172:173], v85 offset0:32 offset1:48
	v_add_u32_e32 v85, 176, v84
	ds_read2st64_b32 v[174:175], v85 offset1:16
	ds_read2st64_b32 v[176:177], v85 offset0:32 offset1:48
	v_add_u32_e32 v85, 184, v84
	ds_read2st64_b32 v[178:179], v85 offset1:16
	ds_read2st64_b32 v[180:181], v85 offset0:32 offset1:48
	s_waitcnt vmcnt(55)
	v_pk_fma_f32 v[10:11], v[94:95], v[182:183], v[10:11] op_sel_hi:[0,1,1]
	v_pk_fma_f32 v[12:13], v[94:95], v[184:185], v[12:13] op_sel_hi:[0,1,1]
	s_waitcnt vmcnt(54)
	v_pk_fma_f32 v[10:11], v[94:95], v[186:187], v[10:11] op_sel:[1,0,0] op_sel_hi:[1,1,1]
	v_pk_fma_f32 v[12:13], v[94:95], v[188:189], v[12:13] op_sel:[1,0,0] op_sel_hi:[1,1,1]
	s_waitcnt vmcnt(53)
	v_pk_fma_f32 v[10:11], v[96:97], v[190:191], v[10:11] op_sel_hi:[0,1,1]
	v_pk_fma_f32 v[12:13], v[96:97], v[192:193], v[12:13] op_sel_hi:[0,1,1]
	s_waitcnt vmcnt(52)
	v_pk_fma_f32 v[10:11], v[96:97], v[194:195], v[10:11] op_sel:[1,0,0] op_sel_hi:[1,1,1]
	v_pk_fma_f32 v[12:13], v[96:97], v[196:197], v[12:13] op_sel:[1,0,0] op_sel_hi:[1,1,1]
	s_waitcnt vmcnt(51)
	v_pk_fma_f32 v[10:11], v[98:99], v[198:199], v[10:11] op_sel_hi:[0,1,1]
	v_pk_fma_f32 v[12:13], v[98:99], v[200:201], v[12:13] op_sel_hi:[0,1,1]
	s_waitcnt vmcnt(50)
	v_pk_fma_f32 v[10:11], v[98:99], v[202:203], v[10:11] op_sel:[1,0,0] op_sel_hi:[1,1,1]
	v_pk_fma_f32 v[12:13], v[98:99], v[204:205], v[12:13] op_sel:[1,0,0] op_sel_hi:[1,1,1]
	s_waitcnt vmcnt(49)
	v_pk_fma_f32 v[10:11], v[100:101], v[206:207], v[10:11] op_sel_hi:[0,1,1]
	v_pk_fma_f32 v[12:13], v[100:101], v[208:209], v[12:13] op_sel_hi:[0,1,1]
	s_waitcnt vmcnt(48)
	v_pk_fma_f32 v[10:11], v[100:101], v[210:211], v[10:11] op_sel:[1,0,0] op_sel_hi:[1,1,1]
	v_pk_fma_f32 v[12:13], v[100:101], v[212:213], v[12:13] op_sel:[1,0,0] op_sel_hi:[1,1,1]
	s_waitcnt lgkmcnt(0)
	v_add_u32_e32 v85, 192, v84
	ds_read2st64_b32 v[182:183], v85 offset1:16
	ds_read2st64_b32 v[184:185], v85 offset0:32 offset1:48
	v_add_u32_e32 v85, 200, v84
	ds_read2st64_b32 v[186:187], v85 offset1:16
	ds_read2st64_b32 v[188:189], v85 offset0:32 offset1:48
	v_add_u32_e32 v85, 208, v84
	ds_read2st64_b32 v[190:191], v85 offset1:16
	ds_read2st64_b32 v[192:193], v85 offset0:32 offset1:48
	v_add_u32_e32 v85, 216, v84
	ds_read2st64_b32 v[194:195], v85 offset1:16
	ds_read2st64_b32 v[196:197], v85 offset0:32 offset1:48
	v_add_u32_e32 v85, 224, v84
	ds_read2st64_b32 v[198:199], v85 offset1:16
	ds_read2st64_b32 v[200:201], v85 offset0:32 offset1:48
	v_add_u32_e32 v85, 232, v84
	ds_read2st64_b32 v[202:203], v85 offset1:16
	ds_read2st64_b32 v[204:205], v85 offset0:32 offset1:48
	v_add_u32_e32 v85, 240, v84
	ds_read2st64_b32 v[206:207], v85 offset1:16
	ds_read2st64_b32 v[208:209], v85 offset0:32 offset1:48
	v_add_u32_e32 v85, 248, v84
	ds_read2st64_b32 v[210:211], v85 offset1:16
	ds_read2st64_b32 v[212:213], v85 offset0:32 offset1:48
	s_waitcnt vmcnt(47)
	v_pk_fma_f32 v[10:11], v[102:103], v[150:151], v[10:11] op_sel_hi:[0,1,1]
	v_pk_fma_f32 v[12:13], v[102:103], v[152:153], v[12:13] op_sel_hi:[0,1,1]
	s_waitcnt vmcnt(46)
	v_pk_fma_f32 v[10:11], v[102:103], v[154:155], v[10:11] op_sel:[1,0,0] op_sel_hi:[1,1,1]
	v_pk_fma_f32 v[12:13], v[102:103], v[156:157], v[12:13] op_sel:[1,0,0] op_sel_hi:[1,1,1]
	s_waitcnt vmcnt(45)
	v_pk_fma_f32 v[10:11], v[104:105], v[158:159], v[10:11] op_sel_hi:[0,1,1]
	v_pk_fma_f32 v[12:13], v[104:105], v[160:161], v[12:13] op_sel_hi:[0,1,1]
	s_waitcnt vmcnt(44)
	v_pk_fma_f32 v[10:11], v[104:105], v[162:163], v[10:11] op_sel:[1,0,0] op_sel_hi:[1,1,1]
	v_pk_fma_f32 v[12:13], v[104:105], v[164:165], v[12:13] op_sel:[1,0,0] op_sel_hi:[1,1,1]
	s_waitcnt vmcnt(43)
	v_pk_fma_f32 v[10:11], v[106:107], v[166:167], v[10:11] op_sel_hi:[0,1,1]
	v_pk_fma_f32 v[12:13], v[106:107], v[168:169], v[12:13] op_sel_hi:[0,1,1]
	s_waitcnt vmcnt(42)
	v_pk_fma_f32 v[10:11], v[106:107], v[170:171], v[10:11] op_sel:[1,0,0] op_sel_hi:[1,1,1]
	v_pk_fma_f32 v[12:13], v[106:107], v[172:173], v[12:13] op_sel:[1,0,0] op_sel_hi:[1,1,1]
	s_waitcnt vmcnt(41)
	v_pk_fma_f32 v[10:11], v[108:109], v[174:175], v[10:11] op_sel_hi:[0,1,1]
	v_pk_fma_f32 v[12:13], v[108:109], v[176:177], v[12:13] op_sel_hi:[0,1,1]
	s_waitcnt vmcnt(40)
	v_pk_fma_f32 v[10:11], v[108:109], v[178:179], v[10:11] op_sel:[1,0,0] op_sel_hi:[1,1,1]
	v_pk_fma_f32 v[12:13], v[108:109], v[180:181], v[12:13] op_sel:[1,0,0] op_sel_hi:[1,1,1]
	s_waitcnt lgkmcnt(0)
	v_add_u32_e32 v85, 256, v84
	ds_read2st64_b32 v[150:151], v85 offset1:16
	ds_read2st64_b32 v[152:153], v85 offset0:32 offset1:48
	v_add_u32_e32 v85, 264, v84
	ds_read2st64_b32 v[154:155], v85 offset1:16
	ds_read2st64_b32 v[156:157], v85 offset0:32 offset1:48
	v_add_u32_e32 v85, 272, v84
	ds_read2st64_b32 v[158:159], v85 offset1:16
	ds_read2st64_b32 v[160:161], v85 offset0:32 offset1:48
	v_add_u32_e32 v85, 280, v84
	ds_read2st64_b32 v[162:163], v85 offset1:16
	ds_read2st64_b32 v[164:165], v85 offset0:32 offset1:48
	v_add_u32_e32 v85, 288, v84
	ds_read2st64_b32 v[166:167], v85 offset1:16
	ds_read2st64_b32 v[168:169], v85 offset0:32 offset1:48
	v_add_u32_e32 v85, 296, v84
	ds_read2st64_b32 v[170:171], v85 offset1:16
	ds_read2st64_b32 v[172:173], v85 offset0:32 offset1:48
	v_add_u32_e32 v85, 304, v84
	ds_read2st64_b32 v[174:175], v85 offset1:16
	ds_read2st64_b32 v[176:177], v85 offset0:32 offset1:48
	v_add_u32_e32 v85, 312, v84
	ds_read2st64_b32 v[178:179], v85 offset1:16
	ds_read2st64_b32 v[180:181], v85 offset0:32 offset1:48
	s_waitcnt vmcnt(39)
	v_pk_fma_f32 v[10:11], v[110:111], v[182:183], v[10:11] op_sel_hi:[0,1,1]
	v_pk_fma_f32 v[12:13], v[110:111], v[184:185], v[12:13] op_sel_hi:[0,1,1]
	s_waitcnt vmcnt(38)
	v_pk_fma_f32 v[10:11], v[110:111], v[186:187], v[10:11] op_sel:[1,0,0] op_sel_hi:[1,1,1]
	v_pk_fma_f32 v[12:13], v[110:111], v[188:189], v[12:13] op_sel:[1,0,0] op_sel_hi:[1,1,1]
	s_waitcnt vmcnt(37)
	v_pk_fma_f32 v[10:11], v[112:113], v[190:191], v[10:11] op_sel_hi:[0,1,1]
	v_pk_fma_f32 v[12:13], v[112:113], v[192:193], v[12:13] op_sel_hi:[0,1,1]
	s_waitcnt vmcnt(36)
	v_pk_fma_f32 v[10:11], v[112:113], v[194:195], v[10:11] op_sel:[1,0,0] op_sel_hi:[1,1,1]
	v_pk_fma_f32 v[12:13], v[112:113], v[196:197], v[12:13] op_sel:[1,0,0] op_sel_hi:[1,1,1]
	s_waitcnt vmcnt(35)
	v_pk_fma_f32 v[10:11], v[114:115], v[198:199], v[10:11] op_sel_hi:[0,1,1]
	v_pk_fma_f32 v[12:13], v[114:115], v[200:201], v[12:13] op_sel_hi:[0,1,1]
	s_waitcnt vmcnt(34)
	v_pk_fma_f32 v[10:11], v[114:115], v[202:203], v[10:11] op_sel:[1,0,0] op_sel_hi:[1,1,1]
	v_pk_fma_f32 v[12:13], v[114:115], v[204:205], v[12:13] op_sel:[1,0,0] op_sel_hi:[1,1,1]
	s_waitcnt vmcnt(33)
	v_pk_fma_f32 v[10:11], v[116:117], v[206:207], v[10:11] op_sel_hi:[0,1,1]
	v_pk_fma_f32 v[12:13], v[116:117], v[208:209], v[12:13] op_sel_hi:[0,1,1]
	s_waitcnt vmcnt(32)
	v_pk_fma_f32 v[10:11], v[116:117], v[210:211], v[10:11] op_sel:[1,0,0] op_sel_hi:[1,1,1]
	v_pk_fma_f32 v[12:13], v[116:117], v[212:213], v[12:13] op_sel:[1,0,0] op_sel_hi:[1,1,1]
	s_waitcnt lgkmcnt(0)
	v_add_u32_e32 v85, 320, v84
	ds_read2st64_b32 v[182:183], v85 offset1:16
	ds_read2st64_b32 v[184:185], v85 offset0:32 offset1:48
	v_add_u32_e32 v85, 328, v84
	ds_read2st64_b32 v[186:187], v85 offset1:16
	ds_read2st64_b32 v[188:189], v85 offset0:32 offset1:48
	v_add_u32_e32 v85, 336, v84
	ds_read2st64_b32 v[190:191], v85 offset1:16
	ds_read2st64_b32 v[192:193], v85 offset0:32 offset1:48
	v_add_u32_e32 v85, 344, v84
	ds_read2st64_b32 v[194:195], v85 offset1:16
	ds_read2st64_b32 v[196:197], v85 offset0:32 offset1:48
	v_add_u32_e32 v85, 352, v84
	ds_read2st64_b32 v[198:199], v85 offset1:16
	ds_read2st64_b32 v[200:201], v85 offset0:32 offset1:48
	v_add_u32_e32 v85, 360, v84
	ds_read2st64_b32 v[202:203], v85 offset1:16
	ds_read2st64_b32 v[204:205], v85 offset0:32 offset1:48
	v_add_u32_e32 v85, 368, v84
	ds_read2st64_b32 v[206:207], v85 offset1:16
	ds_read2st64_b32 v[208:209], v85 offset0:32 offset1:48
	v_add_u32_e32 v85, 376, v84
	ds_read2st64_b32 v[210:211], v85 offset1:16
	ds_read2st64_b32 v[212:213], v85 offset0:32 offset1:48
	s_waitcnt vmcnt(31)
	v_pk_fma_f32 v[10:11], v[118:119], v[150:151], v[10:11] op_sel_hi:[0,1,1]
	v_pk_fma_f32 v[12:13], v[118:119], v[152:153], v[12:13] op_sel_hi:[0,1,1]
	s_waitcnt vmcnt(30)
	v_pk_fma_f32 v[10:11], v[118:119], v[154:155], v[10:11] op_sel:[1,0,0] op_sel_hi:[1,1,1]
	v_pk_fma_f32 v[12:13], v[118:119], v[156:157], v[12:13] op_sel:[1,0,0] op_sel_hi:[1,1,1]
	s_waitcnt vmcnt(29)
	v_pk_fma_f32 v[10:11], v[120:121], v[158:159], v[10:11] op_sel_hi:[0,1,1]
	v_pk_fma_f32 v[12:13], v[120:121], v[160:161], v[12:13] op_sel_hi:[0,1,1]
	s_waitcnt vmcnt(28)
	v_pk_fma_f32 v[10:11], v[120:121], v[162:163], v[10:11] op_sel:[1,0,0] op_sel_hi:[1,1,1]
	v_pk_fma_f32 v[12:13], v[120:121], v[164:165], v[12:13] op_sel:[1,0,0] op_sel_hi:[1,1,1]
	s_waitcnt vmcnt(27)
	v_pk_fma_f32 v[10:11], v[122:123], v[166:167], v[10:11] op_sel_hi:[0,1,1]
	v_pk_fma_f32 v[12:13], v[122:123], v[168:169], v[12:13] op_sel_hi:[0,1,1]
	s_waitcnt vmcnt(26)
	v_pk_fma_f32 v[10:11], v[122:123], v[170:171], v[10:11] op_sel:[1,0,0] op_sel_hi:[1,1,1]
	v_pk_fma_f32 v[12:13], v[122:123], v[172:173], v[12:13] op_sel:[1,0,0] op_sel_hi:[1,1,1]
	s_waitcnt vmcnt(25)
	v_pk_fma_f32 v[10:11], v[124:125], v[174:175], v[10:11] op_sel_hi:[0,1,1]
	v_pk_fma_f32 v[12:13], v[124:125], v[176:177], v[12:13] op_sel_hi:[0,1,1]
	s_waitcnt vmcnt(24)
	v_pk_fma_f32 v[10:11], v[124:125], v[178:179], v[10:11] op_sel:[1,0,0] op_sel_hi:[1,1,1]
	v_pk_fma_f32 v[12:13], v[124:125], v[180:181], v[12:13] op_sel:[1,0,0] op_sel_hi:[1,1,1]
	s_waitcnt lgkmcnt(0)
	v_add_u32_e32 v85, 384, v84
	ds_read2st64_b32 v[150:151], v85 offset1:16
	ds_read2st64_b32 v[152:153], v85 offset0:32 offset1:48
	v_add_u32_e32 v85, 392, v84
	ds_read2st64_b32 v[154:155], v85 offset1:16
	ds_read2st64_b32 v[156:157], v85 offset0:32 offset1:48
	v_add_u32_e32 v85, 400, v84
	ds_read2st64_b32 v[158:159], v85 offset1:16
	ds_read2st64_b32 v[160:161], v85 offset0:32 offset1:48
	v_add_u32_e32 v85, 408, v84
	ds_read2st64_b32 v[162:163], v85 offset1:16
	ds_read2st64_b32 v[164:165], v85 offset0:32 offset1:48
	v_add_u32_e32 v85, 416, v84
	ds_read2st64_b32 v[166:167], v85 offset1:16
	ds_read2st64_b32 v[168:169], v85 offset0:32 offset1:48
	v_add_u32_e32 v85, 424, v84
	ds_read2st64_b32 v[170:171], v85 offset1:16
	ds_read2st64_b32 v[172:173], v85 offset0:32 offset1:48
	v_add_u32_e32 v85, 432, v84
	ds_read2st64_b32 v[174:175], v85 offset1:16
	ds_read2st64_b32 v[176:177], v85 offset0:32 offset1:48
	v_add_u32_e32 v85, 440, v84
	ds_read2st64_b32 v[178:179], v85 offset1:16
	ds_read2st64_b32 v[180:181], v85 offset0:32 offset1:48
	s_waitcnt vmcnt(23)
	v_pk_fma_f32 v[10:11], v[126:127], v[182:183], v[10:11] op_sel_hi:[0,1,1]
	v_pk_fma_f32 v[12:13], v[126:127], v[184:185], v[12:13] op_sel_hi:[0,1,1]
	s_waitcnt vmcnt(22)
	v_pk_fma_f32 v[10:11], v[126:127], v[186:187], v[10:11] op_sel:[1,0,0] op_sel_hi:[1,1,1]
	v_pk_fma_f32 v[12:13], v[126:127], v[188:189], v[12:13] op_sel:[1,0,0] op_sel_hi:[1,1,1]
	s_waitcnt vmcnt(21)
	v_pk_fma_f32 v[10:11], v[128:129], v[190:191], v[10:11] op_sel_hi:[0,1,1]
	v_pk_fma_f32 v[12:13], v[128:129], v[192:193], v[12:13] op_sel_hi:[0,1,1]
	s_waitcnt vmcnt(20)
	v_pk_fma_f32 v[10:11], v[128:129], v[194:195], v[10:11] op_sel:[1,0,0] op_sel_hi:[1,1,1]
	v_pk_fma_f32 v[12:13], v[128:129], v[196:197], v[12:13] op_sel:[1,0,0] op_sel_hi:[1,1,1]
	s_waitcnt vmcnt(19)
	v_pk_fma_f32 v[10:11], v[130:131], v[198:199], v[10:11] op_sel_hi:[0,1,1]
	v_pk_fma_f32 v[12:13], v[130:131], v[200:201], v[12:13] op_sel_hi:[0,1,1]
	s_waitcnt vmcnt(18)
	v_pk_fma_f32 v[10:11], v[130:131], v[202:203], v[10:11] op_sel:[1,0,0] op_sel_hi:[1,1,1]
	v_pk_fma_f32 v[12:13], v[130:131], v[204:205], v[12:13] op_sel:[1,0,0] op_sel_hi:[1,1,1]
	s_waitcnt vmcnt(17)
	v_pk_fma_f32 v[10:11], v[132:133], v[206:207], v[10:11] op_sel_hi:[0,1,1]
	v_pk_fma_f32 v[12:13], v[132:133], v[208:209], v[12:13] op_sel_hi:[0,1,1]
	s_waitcnt vmcnt(16)
	v_pk_fma_f32 v[10:11], v[132:133], v[210:211], v[10:11] op_sel:[1,0,0] op_sel_hi:[1,1,1]
	v_pk_fma_f32 v[12:13], v[132:133], v[212:213], v[12:13] op_sel:[1,0,0] op_sel_hi:[1,1,1]
	s_waitcnt lgkmcnt(0)
	v_add_u32_e32 v85, 448, v84
	ds_read2st64_b32 v[182:183], v85 offset1:16
	ds_read2st64_b32 v[184:185], v85 offset0:32 offset1:48
	v_add_u32_e32 v85, 456, v84
	ds_read2st64_b32 v[186:187], v85 offset1:16
	ds_read2st64_b32 v[188:189], v85 offset0:32 offset1:48
	v_add_u32_e32 v85, 464, v84
	ds_read2st64_b32 v[190:191], v85 offset1:16
	ds_read2st64_b32 v[192:193], v85 offset0:32 offset1:48
	v_add_u32_e32 v85, 472, v84
	ds_read2st64_b32 v[194:195], v85 offset1:16
	ds_read2st64_b32 v[196:197], v85 offset0:32 offset1:48
	v_add_u32_e32 v85, 480, v84
	ds_read2st64_b32 v[198:199], v85 offset1:16
	ds_read2st64_b32 v[200:201], v85 offset0:32 offset1:48
	v_add_u32_e32 v85, 488, v84
	ds_read2st64_b32 v[202:203], v85 offset1:16
	ds_read2st64_b32 v[204:205], v85 offset0:32 offset1:48
	v_add_u32_e32 v85, 496, v84
	ds_read2st64_b32 v[206:207], v85 offset1:16
	ds_read2st64_b32 v[208:209], v85 offset0:32 offset1:48
	v_add_u32_e32 v85, 504, v84
	ds_read2st64_b32 v[210:211], v85 offset1:16
	ds_read2st64_b32 v[212:213], v85 offset0:32 offset1:48
	s_waitcnt vmcnt(15)
	v_pk_fma_f32 v[10:11], v[134:135], v[150:151], v[10:11] op_sel_hi:[0,1,1]
	v_pk_fma_f32 v[12:13], v[134:135], v[152:153], v[12:13] op_sel_hi:[0,1,1]
	s_waitcnt vmcnt(14)
	v_pk_fma_f32 v[10:11], v[134:135], v[154:155], v[10:11] op_sel:[1,0,0] op_sel_hi:[1,1,1]
	v_pk_fma_f32 v[12:13], v[134:135], v[156:157], v[12:13] op_sel:[1,0,0] op_sel_hi:[1,1,1]
	s_waitcnt vmcnt(13)
	v_pk_fma_f32 v[10:11], v[136:137], v[158:159], v[10:11] op_sel_hi:[0,1,1]
	v_pk_fma_f32 v[12:13], v[136:137], v[160:161], v[12:13] op_sel_hi:[0,1,1]
	s_waitcnt vmcnt(12)
	v_pk_fma_f32 v[10:11], v[136:137], v[162:163], v[10:11] op_sel:[1,0,0] op_sel_hi:[1,1,1]
	v_pk_fma_f32 v[12:13], v[136:137], v[164:165], v[12:13] op_sel:[1,0,0] op_sel_hi:[1,1,1]
	s_waitcnt vmcnt(11)
	v_pk_fma_f32 v[10:11], v[138:139], v[166:167], v[10:11] op_sel_hi:[0,1,1]
	v_pk_fma_f32 v[12:13], v[138:139], v[168:169], v[12:13] op_sel_hi:[0,1,1]
	s_waitcnt vmcnt(10)
	v_pk_fma_f32 v[10:11], v[138:139], v[170:171], v[10:11] op_sel:[1,0,0] op_sel_hi:[1,1,1]
	v_pk_fma_f32 v[12:13], v[138:139], v[172:173], v[12:13] op_sel:[1,0,0] op_sel_hi:[1,1,1]
	s_waitcnt vmcnt(9)
	v_pk_fma_f32 v[10:11], v[140:141], v[174:175], v[10:11] op_sel_hi:[0,1,1]
	v_pk_fma_f32 v[12:13], v[140:141], v[176:177], v[12:13] op_sel_hi:[0,1,1]
	s_waitcnt vmcnt(8)
	v_pk_fma_f32 v[10:11], v[140:141], v[178:179], v[10:11] op_sel:[1,0,0] op_sel_hi:[1,1,1]
	v_pk_fma_f32 v[12:13], v[140:141], v[180:181], v[12:13] op_sel:[1,0,0] op_sel_hi:[1,1,1]
	s_waitcnt lgkmcnt(0)
	s_waitcnt vmcnt(7)
	v_pk_fma_f32 v[10:11], v[142:143], v[182:183], v[10:11] op_sel_hi:[0,1,1]
	v_pk_fma_f32 v[12:13], v[142:143], v[184:185], v[12:13] op_sel_hi:[0,1,1]
	s_waitcnt vmcnt(6)
	v_pk_fma_f32 v[10:11], v[142:143], v[186:187], v[10:11] op_sel:[1,0,0] op_sel_hi:[1,1,1]
	v_pk_fma_f32 v[12:13], v[142:143], v[188:189], v[12:13] op_sel:[1,0,0] op_sel_hi:[1,1,1]
	s_waitcnt vmcnt(5)
	v_pk_fma_f32 v[10:11], v[144:145], v[190:191], v[10:11] op_sel_hi:[0,1,1]
	v_pk_fma_f32 v[12:13], v[144:145], v[192:193], v[12:13] op_sel_hi:[0,1,1]
	s_waitcnt vmcnt(4)
	v_pk_fma_f32 v[10:11], v[144:145], v[194:195], v[10:11] op_sel:[1,0,0] op_sel_hi:[1,1,1]
	v_pk_fma_f32 v[12:13], v[144:145], v[196:197], v[12:13] op_sel:[1,0,0] op_sel_hi:[1,1,1]
	s_waitcnt vmcnt(3)
	v_pk_fma_f32 v[10:11], v[146:147], v[198:199], v[10:11] op_sel_hi:[0,1,1]
	v_pk_fma_f32 v[12:13], v[146:147], v[200:201], v[12:13] op_sel_hi:[0,1,1]
	s_waitcnt vmcnt(2)
	v_pk_fma_f32 v[10:11], v[146:147], v[202:203], v[10:11] op_sel:[1,0,0] op_sel_hi:[1,1,1]
	v_pk_fma_f32 v[12:13], v[146:147], v[204:205], v[12:13] op_sel:[1,0,0] op_sel_hi:[1,1,1]
	s_waitcnt vmcnt(1)
	v_pk_fma_f32 v[10:11], v[148:149], v[206:207], v[10:11] op_sel_hi:[0,1,1]
	v_pk_fma_f32 v[12:13], v[148:149], v[208:209], v[12:13] op_sel_hi:[0,1,1]
	s_waitcnt vmcnt(0)
	v_pk_fma_f32 v[10:11], v[148:149], v[210:211], v[10:11] op_sel:[1,0,0] op_sel_hi:[1,1,1]
	v_pk_fma_f32 v[12:13], v[148:149], v[212:213], v[12:13] op_sel:[1,0,0] op_sel_hi:[1,1,1]

.LBB0_640:
	v_mov_b32_e32 v1, v218
	s_cmpk_gt_i32 s15, 0x1ff
	s_barrier
	s_mov_b64 s[0:1], -1
	v_ashrrev_i32_e32 v122, 2, v1
	s_cbranch_scc0 .LBB0_664
	v_and_b32_e32 v124, 15, v1
	s_and_b32 s20, s15, 7
	v_and_b32_e32 v28, 0xffffffc0, v122
	s_lshl_b32 s0, s20, 15
	v_or_b32_e32 v118, v28, v124
	s_add_u32 s0, s6, s0
	v_ashrrev_i32_e32 v119, 31, v118
	v_bfe_u32 v123, v1, 4, 2
	s_addc_u32 s1, s7, 0
	v_lshlrev_b64 v[2:3], 8, v[118:119]
	v_lshl_add_u64 v[2:3], s[0:1], 0, v[2:3]
	v_lshlrev_b32_e32 v114, 4, v123
	v_lshl_add_u64 v[26:27], v[2:3], 0, v[114:115]
	v_add_co_u32_e32 v2, vcc, s9, v26
	v_cmp_lt_u32_e64 s[4:5], s8, v1
	s_nop 0
	v_addc_co_u32_e32 v3, vcc, 0, v27, vcc
	v_add_co_u32_e32 v4, vcc, 0x2000, v26
	s_nop 1
	v_addc_co_u32_e32 v5, vcc, 0, v27, vcc
	v_add_co_u32_e32 v6, vcc, 0x3000, v26
	s_nop 1
	v_addc_co_u32_e32 v7, vcc, 0, v27, vcc
	s_lshl_b32 s98, s20, 7
	v_add_u32_e32 v170, s98, v118
	v_ashrrev_i32_e32 v171, 31, v170
	v_lshl_add_u64 v[170:171], v[170:171], 2, s[18:19]
	global_load_dword v166, v[170:171], off
	global_load_dword v167, v[170:171], off offset:64
	global_load_dword v168, v[170:171], off offset:128
	global_load_dword v169, v[170:171], off offset:192
	global_load_dwordx4 v[34:37], v[26:27], off
	global_load_dwordx4 v[10:13], v[26:27], off offset:64
	global_load_dwordx4 v[38:41], v[2:3], off
	global_load_dwordx4 v[14:17], v[2:3], off offset:64
	global_load_dwordx4 v[42:45], v[4:5], off
	global_load_dwordx4 v[18:21], v[4:5], off offset:64
	global_load_dwordx4 v[30:33], v[6:7], off
	global_load_dwordx4 v[22:25], v[6:7], off offset:64
	v_mov_b32_e32 v6, 0
	v_mov_b32_e32 v2, 0
	v_mov_b32_e32 v3, 0
	v_mov_b32_e32 v4, 0
	v_mov_b32_e32 v5, 0
	s_and_saveexec_b64 s[0:1], s[4:5]
	s_cbranch_execz .LBB0_643
	global_load_dwordx4 v[2:5], v[26:27], off offset:128

.LBB0_663:
	s_or_b64 exec, exec, s[0:1]
	s_lshl_b32 s0, s20, 7
	v_add_u32_e32 v2, s0, v118
	v_ashrrev_i32_e32 v3, 31, v2
	v_lshl_add_u64 v[6:7], v[2:3], 2, s[18:19]
	s_nop 0
	v_add_u32_e32 v8, s21, v118
	v_ashrrev_i32_e32 v9, 31, v8
	v_lshlrev_b64 v[2:3], 11, v[8:9]
	v_lshlrev_b32_e32 v5, 16, v78
	v_and_b32_e32 v24, 0xffff0000, v78
	v_lshlrev_b32_e32 v25, 16, v79
	v_lshl_add_u64 v[22:23], v[116:117], 0, v[2:3]
	v_and_b32_e32 v46, 0xffff0000, v79
	v_lshlrev_b32_e32 v47, 16, v80
	v_and_b32_e32 v48, 0xffff0000, v80
	v_lshlrev_b32_e32 v49, 16, v81
	v_and_b32_e32 v50, 0xffff0000, v81
	s_mov_b64 s[0:1], 0
	s_nop 0
	v_add_f32_e32 v2, v166, v82
	v_add_f32_e32 v3, v166, v83
	v_add_f32_e32 v9, v166, v84
	v_add_f32_e32 v51, v166, v85
	v_add_f32_e32 v42, v42, v166
	v_add_f32_e32 v43, v43, v166
	v_add_f32_e32 v44, v44, v166
	v_add_f32_e32 v4, v45, v166
	v_mul_f32_e32 v2, v2, v5
	v_mul_f32_e32 v3, v3, v24
	v_mul_f32_e32 v5, v9, v25
	v_mul_f32_e32 v9, v51, v46
	v_mul_f32_e32 v24, v42, v47
	v_mul_f32_e32 v25, v43, v48
	v_mul_f32_e32 v42, v44, v49
	v_mul_f32_e32 v43, v4, v50
	v_cvt_pk_bf16_f32 v2, v2, v3
	v_cvt_pk_bf16_f32 v3, v5, v9
	v_cvt_pk_bf16_f32 v4, v24, v25
	v_cvt_pk_bf16_f32 v5, v42, v43
	global_store_dwordx4 v[22:23], v[2:5], off
	s_nop 0
	v_and_b32_e32 v9, 0xffff0000, v74
	v_add_u32_e32 v2, 16, v8
	v_ashrrev_i32_e32 v3, 31, v2
	v_lshlrev_b64 v[2:3], 11, v[2:3]
	v_lshlrev_b32_e32 v5, 16, v74
	v_lshlrev_b32_e32 v24, 16, v75
	v_lshl_add_u64 v[22:23], v[116:117], 0, v[2:3]
	v_and_b32_e32 v25, 0xffff0000, v75
	v_lshlrev_b32_e32 v42, 16, v76
	v_and_b32_e32 v43, 0xffff0000, v76
	v_lshlrev_b32_e32 v44, 16, v77
	v_and_b32_e32 v45, 0xffff0000, v77
	s_nop 0
	v_add_f32_e32 v2, v38, v167
	v_add_f32_e32 v3, v39, v167
	v_add_f32_e32 v38, v40, v167
	v_add_f32_e32 v39, v41, v167
	v_add_f32_e32 v34, v34, v167
	v_add_f32_e32 v35, v35, v167
	v_add_f32_e32 v36, v36, v167
	v_add_f32_e32 v4, v37, v167
	v_mul_f32_e32 v2, v2, v5
	v_mul_f32_e32 v3, v3, v9
	v_mul_f32_e32 v5, v38, v24
	v_mul_f32_e32 v9, v39, v25
	v_mul_f32_e32 v24, v34, v42
	v_mul_f32_e32 v25, v35, v43
	v_mul_f32_e32 v34, v36, v44
	v_mul_f32_e32 v35, v4, v45
	v_cvt_pk_bf16_f32 v2, v2, v3
	v_cvt_pk_bf16_f32 v3, v5, v9
	v_cvt_pk_bf16_f32 v4, v24, v25
	v_cvt_pk_bf16_f32 v5, v34, v35
	global_store_dwordx4 v[22:23], v[2:5], off
	s_nop 0
	v_and_b32_e32 v9, 0xffff0000, v62
	v_add_u32_e32 v2, 32, v8
	v_ashrrev_i32_e32 v3, 31, v2
	v_lshlrev_b64 v[2:3], 11, v[2:3]
	v_lshlrev_b32_e32 v5, 16, v62
	v_lshlrev_b32_e32 v24, 16, v63
	v_lshl_add_u64 v[22:23], v[116:117], 0, v[2:3]
	v_and_b32_e32 v25, 0xffff0000, v63
	v_lshlrev_b32_e32 v34, 16, v64
	v_and_b32_e32 v35, 0xffff0000, v64
	v_lshlrev_b32_e32 v36, 16, v65
	v_and_b32_e32 v37, 0xffff0000, v65
	s_nop 0
	v_add_f32_e32 v2, v30, v168
	v_add_f32_e32 v3, v31, v168
	v_add_f32_e32 v30, v32, v168
	v_add_f32_e32 v31, v33, v168
	v_add_f32_e32 v18, v18, v168
	v_add_f32_e32 v19, v19, v168
	v_add_f32_e32 v20, v20, v168
	v_add_f32_e32 v4, v21, v168
	v_mul_f32_e32 v2, v2, v5
	v_mul_f32_e32 v3, v3, v9
	v_mul_f32_e32 v5, v30, v24
	v_mul_f32_e32 v9, v31, v25
	v_mul_f32_e32 v18, v18, v34
	v_mul_f32_e32 v19, v19, v35
	v_mul_f32_e32 v20, v20, v36
	v_mul_f32_e32 v21, v4, v37
	v_cvt_pk_bf16_f32 v2, v2, v3
	v_cvt_pk_bf16_f32 v3, v5, v9
	v_cvt_pk_bf16_f32 v4, v18, v19
	v_cvt_pk_bf16_f32 v5, v20, v21
	global_store_dwordx4 v[22:23], v[2:5], off
	s_nop 0
	v_add_u32_e32 v6, 48, v8
	v_lshlrev_b32_e32 v3, 16, v26
	v_and_b32_e32 v4, 0xffff0000, v26
	v_lshlrev_b32_e32 v5, 16, v27
	v_and_b32_e32 v7, 0xffff0000, v27
	v_lshlrev_b32_e32 v9, 16, v28
	v_and_b32_e32 v18, 0xffff0000, v28
	v_lshlrev_b32_e32 v19, 16, v29
	v_and_b32_e32 v20, 0xffff0000, v29
	s_nop 0
	v_add_f32_e32 v8, v14, v169
	v_add_f32_e32 v14, v15, v169
	v_add_f32_e32 v15, v16, v169
	v_add_f32_e32 v16, v17, v169
	v_add_f32_e32 v10, v10, v169
	v_add_f32_e32 v11, v11, v169
	v_add_f32_e32 v12, v12, v169
	v_add_f32_e32 v2, v13, v169
	v_mul_f32_e32 v3, v8, v3
	v_mul_f32_e32 v4, v14, v4
	v_mul_f32_e32 v5, v15, v5
	v_mul_f32_e32 v7, v16, v7
	v_mul_f32_e32 v8, v10, v9
	v_mul_f32_e32 v9, v11, v18
	v_mul_f32_e32 v10, v12, v19
	v_mul_f32_e32 v11, v2, v20
	v_cvt_pk_bf16_f32 v2, v3, v4
	v_cvt_pk_bf16_f32 v3, v5, v7
	v_cvt_pk_bf16_f32 v4, v8, v9
	v_cvt_pk_bf16_f32 v5, v10, v11
